# code placement scan on the hot-path layout: attention code +16 bytes (same 8-byte phase), GEMM placement unchanged
# baseline (speedup 1.0000x reference)
; #define ATT_WAIT_BAR() asm volatile("s_waitcnt vmcnt(0) lgkmcnt(0)\n\ts_barrier" ::: "memory")
; DI void attn_phase(const Params& P, char* shm) {
;     ...
;     for (unsigned k = 0; k < 8; ++k) {
;         const unsigned q = (xcd + k) & 7u; unsigned* cnt = P.counter + 16 * q;
;         for (;;) {
;             if (tid == 0) su[0] = atomicAdd(cnt, 1u);
;             ATT_WAIT_BAR();
;             const unsigned ui = su[0];
;             ATT_WAIT_BAR();
;             if (ui >= 384u) break;
;             const unsigned e = P.order[q * 384 + ui]; const int kind = e >> 28, b = (e >> 24) & 15, h = (e >> 16) & 255, qb = e & 0xffff;
.LBB0_316:
	s_nop 0
	s_nop 0
	s_nop 0
	s_nop 0
	s_nop 0
	v_writelane_b32 v255, 0, 61
	s_nop 0
	s_mov_b32 s0, 0x40000000
	v_writelane_b32 v255, s0, 62
	s_nop 0
	v_readlane_b32 s0, v255, 29
	s_add_i32 s0, s1, s0
	v_writelane_b32 v255, s1, 45
	s_and_b32 s0, s0, 7
	s_lshl_b32 s1, s0, 6
	v_readlane_b32 s2, v255, 25
	s_add_u32 s42, s2, s1
	v_readlane_b32 s1, v255, 26
	s_mul_i32 s41, s0, 0x180
	s_addc_u32 s43, s1, 0
	v_writelane_b32 v255, s41, 46
	v_writelane_b32 v255, s42, 47
	s_nop 1
	v_writelane_b32 v255, s43, 48
	s_branch .LBB0_320

; DI void attn_phase(const Params& P, char* shm) {
;     ...
;     __builtin_amdgcn_s_setprio(0);
.LBB0_438:
	s_nop 0
	s_nop 0
	s_nop 0
	s_nop 0
	s_nop 0
	s_nop 0
	s_nop 0
	s_nop 0
	s_nop 0
	s_nop 0
	s_nop 0
	s_nop 0
	s_nop 0
	s_nop 0
	s_setprio 0
	s_mov_b64 s[0:1], 0
